# PH5 dequeue barrier waits on lgkmcnt only (no drain of the previous item's stores)
# speedup vs baseline: 1.0057x; 1.0046x over previous
.LBB0_1844:
	s_or_b64 exec, exec, s[4:5]
	s_waitcnt lgkmcnt(0)
	s_barrier
	ds_read_b32 v0, v196
	s_mov_b64 s[4:5], -1
	s_waitcnt lgkmcnt(0)
	s_barrier
	v_readfirstlane_b32 s34, v0
	s_mov_b32 s99, 1
	s_cmpk_gt_i32 s34, 0x3ff
	s_cbranch_scc1 .LBB0_1839
	s_cmpk_lt_i32 s34, 0x100
	s_cselect_b64 s[4:5], -1, 0
	s_cmpk_gt_i32 s34, 0xff
	s_cselect_b64 s[6:7], -1, 0
	s_mov_b32 s8, 0
	s_and_b64 vcc, exec, s[4:5]
	s_cbranch_vccnz .LBB0_1848
	s_cmpk_lt_u32 s34, 0x180
	s_mov_b32 s8, 1
	s_cbranch_scc1 .LBB0_1848
	s_cmpk_lt_u32 s34, 0x200
	s_cselect_b32 s8, 3, 4
	s_cmpk_gt_u32 s34, 0x1bf
	s_cselect_b32 s8, s8, 2
